# tail balancing: P4 pool GEMM skipped on the 8 workgroups with a 7th KV unit; P0 weight-prep tiles dealt round-robin across jobs
# speedup vs baseline: 1.0217x; 1.0123x over previous
.LBB0_7:
	s_or_b64 exec, exec, s[4:5]
	v_mov_b32_e32 v7, v228
	s_mov_b32 s2, s74
	s_load_dwordx4 s[28:31], s[0:1], 0xa0
	s_load_dwordx4 s[24:27], s[0:1], 0x0
	s_load_dwordx4 s[20:23], s[0:1], 0x20
	s_load_dwordx2 s[4:5], s[0:1], 0x110
	v_lshlrev_b32_e32 v4, 3, v7
	v_ashrrev_i32_e32 v32, 3, v7
	v_and_b32_e32 v4, 56, v4
	v_mul_u32_u24_e32 v5, 0x104, v4
	v_lshlrev_b32_e32 v6, 2, v32
	s_waitcnt lgkmcnt(0)
	s_mov_b32 s3, s4
	v_and_b32_e32 v1, 63, v7
	v_ashrrev_i32_e32 v2, 6, v7
	v_and_b32_e32 v30, 31, v7
	v_add3_u32 v33, 0, v5, v6
	v_lshl_add_u32 v6, s2, 9, v7
	v_lshlrev_b32_e32 v7, 6, v7
	s_movk_i32 s4, 0x104
	s_mov_b32 s5, 0x10000
	s_lshl_b32 s36, s3, 9
	v_lshl_add_u32 v34, s2, 15, v7
	v_ashrrev_i32_e32 v7, 31, v6
	v_lshl_add_u32 v10, v1, 2, 0
	v_cmp_gt_i32_e64 s[8:9], s5, v6
	v_mul_lo_u32 v11, v2, s4
	v_lshl_add_u64 v[8:9], v[6:7], 1, s[54:55]
	s_mov_b64 s[4:5], 0xba0000
	s_ashr_i32 s37, s36, 31
	v_or_b32_e32 v31, 64, v1
	v_ashrrev_i32_e32 v3, 31, v2
	s_mov_b32 s35, 0
	v_mov_b32_e32 v5, 0
	s_lshl_b32 s33, s2, 6
	s_lshl_b32 s50, s3, 6
	s_lshl_b32 s51, s3, 15
	v_lshl_add_u64 v[8:9], v[8:9], 0, s[4:5]
	s_lshl_b64 s[38:39], s[36:37], 1
	s_mov_b64 s[42:43], 0
	s_mov_b64 s[4:5], -1
	s_movk_i32 s37, 0x60
	s_movk_i32 s56, 0xff
	s_movk_i32 s57, 0x5a0
	s_movk_i32 s58, 0x1a0
	v_add_u32_e32 v7, v10, v11
	v_lshlrev_b32_e32 v10, 1, v4
	s_mov_b32 s59, 0xffff
	s_mov_b32 s101, 0
	s_branch .LBB0_9

.LBB0_17:
	s_lshr_b32 s15, s15, 26
	s_add_i32 s15, s17, s15
	s_ashr_i32 s66, s15, 6
	s_mul_i32 s17, s66, s46
	s_mov_b32 s100, s2
	s_cmp_lg_u32 s3, 0x100
	s_cbranch_scc1 .Lp0_norot
	s_sub_i32 s100, s2, s101
	s_and_b32 s100, s100, 0xff
	s_add_i32 s101, s101, s17
	s_and_b32 s101, s101, 0xff
.Lp0_norot:
	s_cmp_ge_i32 s100, s17
	s_cbranch_scc1 .LBB0_10
	s_load_dwordx2 s[46:47], s[12:13], 0x0
	s_add_u32 s12, s60, s4
	s_addc_u32 s13, s61, s5
	s_ashr_i32 s15, s14, 31
	s_lshl_b64 s[4:5], s[14:15], 1
	s_add_u32 s12, s12, s4
	s_addc_u32 s13, s13, s5
	s_ashr_i32 s4, s16, 31
	s_mul_hi_u32 s5, s6, s16
	s_mul_i32 s4, s6, s4
	s_add_i32 s4, s5, s4
	s_mul_i32 s5, s7, s16
	s_add_i32 s5, s4, s5
	s_mul_i32 s4, s6, s16
	s_lshl_b64 s[4:5], s[4:5], 2
	s_waitcnt lgkmcnt(0)
	s_add_u32 s14, s46, s4
	s_addc_u32 s15, s47, s5
	s_cmp_lg_u64 s[48:49], 0
	s_cselect_b64 s[46:47], -1, 0
	s_abs_i32 s34, s66
	v_cvt_f32_u32_e32 v4, s34
	s_sub_i32 s4, 0, s34
	v_lshl_add_u64 v[12:13], v[2:3], 2, s[48:49]
	s_ashr_i32 s64, s66, 31
	v_rcp_iflag_f32_e32 v4, v4
	s_lshl_b32 s67, s100, 6
	s_mov_b32 s68, s100
	v_mul_f32_e32 v4, 0x4f7ffffe, v4
	v_cvt_u32_f32_e32 v4, v4
	s_nop 0
	v_readfirstlane_b32 s5, v4
	s_mul_i32 s4, s4, s5
	s_mul_hi_u32 s4, s5, s4
	s_add_i32 s65, s5, s4
	s_lshl_b32 s4, s66, 6
	s_sub_i32 s66, 0, s4
	s_branch .LBB0_20

.LBB0_908:
	s_mov_b32 s100, s62
	s_mov_b32 s101, s93
	s_cmpk_lg_i32 s93, 0x100
	s_cbranch_scc1 .Lp4_noremap
	s_movk_i32 s101, 0xf8
	s_sub_i32 s100, s62, 8
	s_cmp_lt_u32 s62, 8
	s_cselect_b32 s100, 0x102, s100
.Lp4_noremap:
	v_mov_b32_e32 v6, v228
	s_cmpk_gt_i32 s100, 0x101
	s_nop 0
	v_readfirstlane_b32 s6, v6
	s_cbranch_scc1 .LBB0_920
	v_bfe_i32 v3, v6, 27, 1
	v_lshlrev_b32_e32 v2, 4, v6
	v_lshrrev_b32_e32 v3, 22, v3
	v_add_u32_e32 v3, v2, v3
	v_and_b32_e32 v3, 0xfffffc00, v3
	v_sub_u32_e32 v3, v2, v3
	v_ashrrev_i32_e32 v0, 31, v6
	v_lshrrev_b32_e32 v4, 4, v3
	v_lshrrev_b32_e32 v0, 26, v0
	v_bitop3_b32 v4, v4, v3, 32 bitop3:0x6c
	v_ashrrev_i32_e32 v3, 31, v3
	v_add_u32_e32 v0, v6, v0
	v_lshrrev_b32_e32 v3, 26, v3
	v_ashrrev_i32_e32 v0, 6, v0
	v_add_u32_e32 v3, v4, v3
	v_lshlrev_b32_e32 v5, 3, v0
	v_ashrrev_i32_e32 v3, 6, v3
	v_and_b32_e32 v5, -16, v5
	v_mul_i32_i24_e32 v7, 64, v3
	v_add_u32_e32 v5, v3, v5
	v_sub_u32_e32 v4, v4, v7
	v_mov_b32_e32 v9, 1
	v_lshlrev_b32_e32 v0, 5, v0
	v_ashrrev_i16_sdwa v4, v9, sext(v4) dst_sel:DWORD dst_unused:UNUSED_PAD src0_sel:DWORD src1_sel:BYTE_0
	v_lshlrev_b32_e32 v7, 1, v5
	v_lshrrev_b32_e32 v8, 2, v5
	v_and_b32_e32 v3, 3, v3
	s_mov_b32 s0, 0x7fffe0
	v_and_b32_e32 v0, 32, v0
	v_bfe_i32 v4, v4, 0, 16
	v_and_b32_e32 v7, 24, v7
	v_and_b32_e32 v8, 4, v8
	v_and_or_b32 v3, v5, s0, v3
	v_or3_b32 v3, v3, v8, v7
	v_add_lshl_u32 v4, v0, v4, 1
	v_add_u32_e32 v2, 0x2000, v2
	v_lshl_add_u32 v154, v3, 9, v4
	v_ashrrev_i32_e32 v3, 31, v2
	v_lshrrev_b32_e32 v3, 22, v3
	v_add_u32_e32 v3, v2, v3
	v_ashrrev_i32_e32 v3, 10, v3
	v_lshl_add_u32 v0, v5, 9, v4
	v_mul_i32_i24_e32 v4, 0x400, v3
	v_sub_u32_e32 v2, v2, v4
	v_lshrrev_b32_e32 v4, 4, v2
	v_bitop3_b32 v2, v4, v2, 32 bitop3:0x6c
	v_ashrrev_i32_e32 v5, 31, v2
	v_lshrrev_b32_e32 v5, 26, v5
	s_ashr_i32 s12, s6, 6
	s_ashr_i32 s7, s6, 8
	v_lshlrev_b32_e32 v4, 3, v3
	v_add_u32_e32 v5, v2, v5
	s_lshl_b32 s36, s12, 10
	v_and_b32_e32 v4, -16, v4
	v_ashrrev_i32_e32 v7, 6, v5
	s_add_u32 s37, s76, 0x26252000
	v_add_u32_e32 v4, v7, v4
	v_and_b32_e32 v7, 3, v7
	s_addc_u32 s38, s77, 0
	s_nop 0
	v_and_or_b32 v7, v4, s0, v7
	s_mov_b32 s0, s100
	s_mov_b32 s1, 0
	s_lshl_b64 s[0:1], s[0:1], 17
	s_add_u32 s8, s37, s0
	s_addc_u32 s9, s38, s1
	s_add_u32 s0, s24, 0xba0000
	s_addc_u32 s1, s25, 0
	v_and_b32_e32 v5, 0xc0, v5
	s_add_u32 s4, s24, 0xbb0000
	v_sub_u32_e32 v2, v2, v5
	s_addc_u32 s5, s25, 0
	v_lshlrev_b32_e32 v3, 5, v3
	v_ashrrev_i16_sdwa v2, v9, sext(v2) dst_sel:DWORD dst_unused:UNUSED_PAD src0_sel:DWORD src1_sel:BYTE_0
	v_lshlrev_b32_e32 v5, 1, v4
	v_lshrrev_b32_e32 v8, 2, v4
	s_add_u32 s10, s8, 0x10000
	v_and_b32_e32 v3, 32, v3
	v_bfe_i32 v2, v2, 0, 16
	v_and_b32_e32 v5, 24, v5
	v_and_b32_e32 v8, 4, v8
	s_addc_u32 s11, s9, 0
	s_add_i32 s39, s36, 0
	v_or3_b32 v5, v7, v8, v5
	v_add_lshl_u32 v2, v3, v2, 1
	s_add_i32 m0, s39, 0x10000
	v_lshl_add_u32 v158, v5, 9, v2
	global_load_lds_dwordx4 v154, s[0:1]
	s_add_i32 m0, s39, 0x12000
	s_add_i32 s40, s39, 0x2000
	global_load_lds_dwordx4 v158, s[0:1]
	s_add_i32 m0, s39, 0x14000
	v_lshl_add_u32 v156, v4, 9, v2
	global_load_lds_dwordx4 v154, s[4:5]
	s_add_i32 m0, s39, 0x16000
	s_add_i32 s41, s39, 0x4000
	global_load_lds_dwordx4 v158, s[4:5]
	s_mov_b32 m0, s39
	s_add_i32 s42, s39, 0x6000
	global_load_lds_dwordx4 v0, s[8:9]
	s_mov_b32 m0, s40
	v_mov_b32_e32 v157, v1
	global_load_lds_dwordx4 v156, s[8:9]
	s_mov_b32 m0, s41
	s_cmp_eq_u32 s7, 1
	global_load_lds_dwordx4 v0, s[10:11]
	s_mov_b32 m0, s42
	v_lshl_add_u64 v[2:3], s[8:9], 0, v[0:1]
	global_load_lds_dwordx4 v156, s[10:11]
	s_cselect_b64 s[10:11], -1, 0
	s_cmp_lg_u32 s7, 1
	v_lshl_add_u64 v[4:5], s[8:9], 0, v[156:157]
	s_cbranch_scc1 .LBB0_911
	s_barrier
.LBB0_911:
	v_and_b32_e32 v7, 15, v6
	v_and_b32_e32 v8, 48, v6
	v_lshlrev_b32_e32 v7, 6, v7
	v_lshlrev_b32_e32 v6, 2, v6
	v_or_b32_e32 v9, v7, v8
	s_lshl_b32 s7, s7, 13
	v_and_b32_e32 v6, 32, v6
	v_bitop3_b32 v7, v7, v6, v8 bitop3:0x36
	v_bitop3_b32 v8, v9, s7, v6 bitop3:0xde
	s_lshl_b32 s7, s12, 12
	s_and_b32 s7, s7, 0x3000
	s_add_u32 s12, s24, 0xba0080
	s_addc_u32 s13, s25, 0
	v_mov_b32_e32 v155, v1
	s_add_u32 s14, s24, 0xbb0080
	v_mov_b32_e32 v159, v1
	v_or_b32_e32 v172, s7, v7
	s_addc_u32 s15, s25, 0
	s_add_i32 m0, s39, 0x18000
	v_lshl_add_u64 v[6:7], s[12:13], 0, v[154:155]
	s_waitcnt vmcnt(2)
	s_barrier
	global_load_lds_dwordx4 v[6:7], off
	v_lshl_add_u64 v[6:7], s[12:13], 0, v[158:159]
	s_add_i32 m0, s39, 0x1a000
	s_add_i32 s43, s39, 0x8000
	global_load_lds_dwordx4 v[6:7], off
	v_lshl_add_u64 v[2:3], v[2:3], 0, s[70:71]
	s_mov_b32 m0, s43
	s_add_i32 s44, s39, 0xa000
	global_load_lds_dwordx4 v[2:3], off
	v_lshl_add_u64 v[2:3], v[4:5], 0, s[70:71]
	s_mov_b32 m0, s44
	s_mov_b32 s45, 0
	global_load_lds_dwordx4 v[2:3], off
	s_add_i32 m0, s39, 0x1c000
	v_lshl_add_u64 v[2:3], s[14:15], 0, v[154:155]
	global_load_lds_dwordx4 v[2:3], off
	v_lshl_add_u64 v[2:3], s[14:15], 0, v[158:159]
	s_add_i32 m0, s39, 0x1e000
	s_cmpk_lt_u32 s6, 0x100
	global_load_lds_dwordx4 v[2:3], off
	s_cselect_b64 s[16:17], -1, 0
	s_add_u32 s18, s24, 0xba0100
	s_addc_u32 s19, s25, 0
	s_add_u32 s20, s24, 0xbb0100
	s_addc_u32 s21, s25, 0
	s_add_u32 s22, s24, 0xba0180
	s_waitcnt vmcnt(6)
	s_addc_u32 s23, s25, 0
	s_add_u32 s24, s24, 0xbb0180
	s_addc_u32 s25, s25, 0
	s_add_i32 s26, s101, s100
	v_add_u32_e32 v155, 0, v8
	s_mov_b32 s46, s100
	s_movk_i32 s63, 0xefc0
	s_barrier
	s_branch .LBB0_914
.LBB0_912:
	s_add_i32 s45, s45, 1
	s_mul_i32 s6, s45, s101
	s_add_i32 s46, s6, s100
	s_add_i32 s26, s26, s101
	s_mov_b64 s[6:7], 0
